# k23: k20 with the static priority raise on waves 0-3 instead of 4-7
# speedup vs baseline: 1.0044x; 1.0040x over previous
; __device__ __forceinline__ int opaque_tid() { int t = threadIdx.x; asm volatile("" : "+v"(t)); return t; }
; #define PG8_STAGE(bufoff, gbase, voff) do { _Pragma("unroll") for (int _i = 0; _i < 2; ++_i) \
;         __builtin_amdgcn_global_load_lds((const unsigned*)((const char*)(gbase) + (voff)[_i]), (LAS unsigned*)(lds + (bufoff) + ldsw + _i * 8192), 16, 0, 0); } while (0)
; #define PG8_BAR __builtin_amdgcn_s_barrier()
; template <class Epi>
; __device__ __forceinline__ void gemm_phase(LAS unsigned char* lds, const Gemm g, const Epi& E) {
;     const int tid = opaque_tid(), wid = __builtin_amdgcn_readfirstlane(tid >> 6), lane = tid & 63, wr = wid >> 2, wc = wid & 3, fr = lane & 15, fq = lane >> 4;
;     const int K = g.K, nt = K / BK;
;     StaticOrder S; S.init(g.M, g.N, (int)gridDim.x, (int)blockIdx.x);
;     unsigned voffA[2], voffB[2];
; #pragma unroll
;     for (int i = 0; i < 2; ++i) { int R, C; stage_rc(tid * 16 + i * 8192, R, C); const int Rb = Epi::PERM ? ((R & ~31) + perm32(R & 31)) : R;
;         voffA[i] = (unsigned)(R * g.lda + C) * 2u; voffB[i] = (unsigned)(Rb * g.ldb + C) * 2u; }
;     const size_t kstep = (size_t)(BK * 2);
;     const size_t hstepA = (size_t)HALF * g.lda * 2, hstepB = (size_t)HALF * g.ldb * 2;
;     const size_t tstepA = 2 * hstepA, tstepB = 2 * hstepB;
;     const unsigned ldsw = (unsigned)wid * 1024u;
;     const int aoff = lds_byte(wr * 64 + fr, fq * 8), boff = lds_byte(wc * 32 + fr, fq * 8);
;     ...
;     Unit cur, nxt; int ui = 0;
;     if (!S.next(0, cur)) return;
;     f32x4 acc[2][2][4][2];
; #pragma unroll
;     for (int a = 0; a < 2; ++a)
; #pragma unroll
;         for (int b = 0; b < 2; ++b)
; #pragma unroll
;             for (int m = 0; m < 4; ++m)
; #pragma unroll
;                 for (int n = 0; n < 2; ++n) acc[a][b][m][n] = (f32x4){0.f, 0.f, 0.f, 0.f};
;     bf16x8 At[4][2], B0[2][2], B1[2][2];
;     const char* cA = (const char*)g.A + (size_t)g.mapA.src(cur.pm) * tstepA + (size_t)cur.pn * g.a_pn_step;
;     const char* cB = (const char*)g.Bt + (size_t)g.mapB.src(cur.pn) * tstepB;
;     PG8_STAGE(PG8_SB(0, 0), cB, voffB); PG8_STAGE(PG8_SA(0, 0), cA, voffA); PG8_STAGE(PG8_SB(0, 1), cB + hstepB, voffB); PG8_STAGE(PG8_SA(0, 1), cA + hstepA, voffA);
;     if (wr == 1) PG8_BAR;
.LBB0_286:
	s_or_b64 exec, exec, s[2:3]
	s_and_b64 s[0:1], s[8:9], exec
	s_movk_i32 s0, 0x120
	s_cselect_b32 s7, 0x100, s0
	v_mov_b32_e32 v2, v210
	s_lshl_b32 s76, s7, 2
	s_barrier
	s_cmp_ge_i32 s37, s76
	v_readfirstlane_b32 s2, v2
	s_cbranch_scc1 .LBB0_310
	v_lshlrev_b32_e32 v1, 4, v2
	v_add_u32_e32 v3, 0x2000, v1
	v_ashrrev_i32_e32 v4, 31, v3
	v_lshrrev_b32_e32 v4, 22, v4
	v_add_u32_e32 v4, v3, v4
	v_ashrrev_i32_e32 v4, 10, v4
	v_mul_i32_i24_e32 v6, 0x400, v4
	v_sub_u32_e32 v3, v3, v6
	v_lshrrev_b32_e32 v6, 4, v3
	v_bitop3_b32 v3, v6, v3, 32 bitop3:0x6c
	v_ashrrev_i32_e32 v6, 31, v3
	v_writelane_b32 v255, s10, 30
	v_lshrrev_b32_e32 v6, 26, v6
	v_readlane_b32 s0, v255, 21
	v_add_u32_e32 v6, v3, v6
	v_readlane_b32 s1, v255, 22
	v_lshlrev_b32_e32 v5, 5, v4
	v_ashrrev_i32_e32 v7, 6, v6
	v_and_b32_e32 v6, 0xc0, v6
	v_lshlrev_b32_e32 v4, 3, v4
	s_lshl_b32 s0, s0, 19
	v_readlane_b32 s1, v254, 28
	v_sub_u32_e32 v3, v3, v6
	v_and_b32_e32 v4, -16, v4
	s_add_u32 s13, s1, s0
	v_readlane_b32 s0, v254, 29
	v_and_b32_e32 v5, 32, v5
	v_ashrrev_i16_sdwa v3, v219, sext(v3) dst_sel:DWORD dst_unused:UNUSED_PAD src0_sel:DWORD src1_sel:BYTE_0
	v_add_u32_e32 v4, v7, v4
	s_addc_u32 s25, s0, 0
	s_ashr_i32 s0, s2, 6
	v_add_u32_sdwa v3, v5, sext(v3) dst_sel:DWORD dst_unused:UNUSED_PAD src0_sel:DWORD src1_sel:WORD_0
	v_lshlrev_b32_e32 v5, 9, v4
	s_ashr_i32 s1, s2, 8
	s_lshl_b32 s30, s0, 10
	v_lshl_add_u32 v146, v3, 1, v5
	s_movk_i32 s11, 0x600
	v_writelane_b32 v255, s2, 31
	s_and_b64 s[2:3], s[8:9], exec
	v_mad_u64_u32 v[148:149], s[2:3], v4, s11, v[146:147]
	v_bfe_i32 v5, v2, 27, 1
	s_cselect_b32 s31, 0, 2.0
	v_lshrrev_b32_e32 v5, 22, v5
	s_lshr_b32 s3, s7, 1
	v_readlane_b32 s2, v254, 49
	v_add_u32_e32 v5, v1, v5
	s_or_b32 s2, s3, s2
	v_and_b32_e32 v5, 0xfffffc00, v5
	s_mul_i32 s2, s2, s80
	v_sub_u32_e32 v1, v1, v5
	s_add_i32 s4, s2, s75
	v_lshrrev_b32_e32 v5, 4, v1
	s_ashr_i32 s2, s4, 31
	v_bitop3_b32 v5, v5, v1, 32 bitop3:0x6c
	v_ashrrev_i32_e32 v1, 31, v1
	s_lshr_b32 s2, s2, 28
	v_ashrrev_i32_e32 v3, 31, v2
	v_lshrrev_b32_e32 v1, 26, v1
	s_add_i32 s5, s4, s2
	v_lshrrev_b32_e32 v3, 26, v3
	v_add_u32_e32 v1, v5, v1
	s_ashr_i32 s2, s5, 4
	v_add_u32_e32 v3, v2, v3
	v_ashrrev_i32_e32 v1, 6, v1
	s_lshl_b32 s6, s2, 2
	v_ashrrev_i32_e32 v3, 6, v3
	v_mul_i32_i24_e32 v6, 64, v1
	v_writelane_b32 v255, s3, 29
	s_sub_i32 s2, s7, s6
	v_lshlrev_b32_e32 v4, 5, v3
	v_sub_u32_e32 v5, v5, v6
	v_writelane_b32 v255, s7, 28
	s_min_i32 s7, s2, 4
	v_and_b32_e32 v4, 32, v4
	v_ashrrev_i16_sdwa v5, v219, sext(v5) dst_sel:DWORD dst_unused:UNUSED_PAD src0_sel:DWORD src1_sel:BYTE_0
	v_lshlrev_b32_e32 v3, 3, v3
	s_abs_i32 s10, s7
	v_add_u32_sdwa v4, v4, sext(v5) dst_sel:DWORD dst_unused:UNUSED_PAD src0_sel:DWORD src1_sel:WORD_0
	v_and_b32_e32 v3, -16, v3
	v_cvt_f32_u32_e32 v5, s10
	v_add_u32_e32 v1, v1, v3
	v_lshlrev_b32_e32 v3, 9, v1
	v_lshl_add_u32 v150, v4, 1, v3
	v_mad_u64_u32 v[152:153], s[2:3], v1, s11, v[150:151]
	v_rcp_iflag_f32_e32 v1, v5
	s_and_b32 s2, s5, -16
	s_sub_i32 s5, 0, s10
	s_sub_i32 s2, s4, s2
	v_mul_f32_e32 v1, 0x4f7ffffe, v1
	v_cvt_u32_f32_e32 v1, v1
	s_abs_i32 s4, s2
	s_xor_b32 s3, s2, s7
	s_ashr_i32 s3, s3, 31
	v_readfirstlane_b32 s11, v1
	s_mul_i32 s5, s5, s11
	s_mul_hi_u32 s5, s11, s5
	s_add_i32 s11, s11, s5
	s_mul_hi_u32 s5, s4, s11
	s_mul_i32 s11, s5, s10
	s_sub_i32 s4, s4, s11
	s_add_i32 s11, s5, 1
	s_sub_i32 s12, s4, s10
	s_cmp_ge_u32 s4, s10
	s_cselect_b32 s5, s11, s5
	s_cselect_b32 s4, s12, s4
	s_add_i32 s11, s5, 1
	s_cmp_ge_u32 s4, s10
	s_cselect_b32 s4, s11, s5
	s_xor_b32 s4, s4, s3
	s_sub_i32 s4, s4, s3
	s_mul_i32 s3, s4, s7
	s_sub_i32 s2, s2, s3
	s_add_i32 s93, s6, s2
	s_and_b64 s[2:3], s[8:9], exec
	s_cselect_b32 s44, 32, -2.0
	s_cmp_ge_i32 s93, s31
	s_cselect_b32 s2, s44, 0
	s_add_i32 s2, s2, s93
	s_ashr_i32 s3, s2, 31
	s_ashr_i32 s5, s4, 31
	s_lshl_b64 s[2:3], s[2:3], 19
	s_lshl_b64 s[6:7], s[4:5], 9
	s_lshl_b64 s[8:9], s[4:5], 17
	s_add_u32 s14, s13, s8
	s_addc_u32 s15, s25, s9
	s_add_i32 s26, s30, 0
	s_add_i32 m0, s26, 0x10000
	s_mov_b32 s91, s13
	global_load_lds_dwordx4 v150, s[14:15]
	s_add_i32 m0, s26, 0x12000
	s_add_u32 s2, s34, s2
	s_addc_u32 s3, s35, s3
	s_add_u32 s16, s2, s6
	global_load_lds_dwordx4 v146, s[14:15]
	s_addc_u32 s17, s3, s7
	s_mov_b32 m0, s26
	s_add_i32 s52, s26, 0x2000
	global_load_lds_dwordx4 v152, s[16:17]
	s_mov_b32 m0, s52
	s_add_u32 s2, s14, 0x10000
	global_load_lds_dwordx4 v148, s[16:17]
	s_addc_u32 s3, s15, 0
	s_add_i32 m0, s26, 0x14000
	s_nop 0
	global_load_lds_dwordx4 v150, s[2:3]
	s_add_i32 m0, s26, 0x16000
	s_nop 0
	global_load_lds_dwordx4 v146, s[2:3]
	s_add_u32 s2, s16, 0x40000
	s_addc_u32 s3, s17, 0
	s_add_i32 s53, s26, 0x4000
	s_mov_b32 m0, s53
	s_add_i32 s68, s26, 0x6000
	global_load_lds_dwordx4 v152, s[2:3]
	s_mov_b32 m0, s68
	s_cmp_lg_u32 s1, 1
	global_load_lds_dwordx4 v148, s[2:3]
	s_setprio 1
	s_cbranch_scc1 .LBB0_289
	s_barrier
	s_setprio 0

; __device__ __forceinline__ int opaque_tid() { int t = threadIdx.x; asm volatile("" : "+v"(t)); return t; }
; #define PG8_STAGE(bufoff, gbase, voff) do { _Pragma("unroll") for (int _i = 0; _i < 2; ++_i) \
;         __builtin_amdgcn_global_load_lds((const unsigned*)((const char*)(gbase) + (voff)[_i]), (LAS unsigned*)(lds + (bufoff) + ldsw + _i * 8192), 16, 0, 0); } while (0)
; #define PG8_BAR __builtin_amdgcn_s_barrier()
; template <class Epi>
; __device__ __forceinline__ void gemm_phase(LAS unsigned char* lds, const Gemm g, const Epi& E) {
;     const int tid = opaque_tid(), wid = __builtin_amdgcn_readfirstlane(tid >> 6), lane = tid & 63, wr = wid >> 2, wc = wid & 3, fr = lane & 15, fq = lane >> 4;
;     const int K = g.K, nt = K / BK;
;     StaticOrder S; S.init(g.M, g.N, (int)gridDim.x, (int)blockIdx.x);
;     unsigned voffA[2], voffB[2];
; #pragma unroll
;     for (int i = 0; i < 2; ++i) { int R, C; stage_rc(tid * 16 + i * 8192, R, C); const int Rb = Epi::PERM ? ((R & ~31) + perm32(R & 31)) : R;
;         voffA[i] = (unsigned)(R * g.lda + C) * 2u; voffB[i] = (unsigned)(Rb * g.ldb + C) * 2u; }
;     const size_t kstep = (size_t)(BK * 2);
;     const size_t hstepA = (size_t)HALF * g.lda * 2, hstepB = (size_t)HALF * g.ldb * 2;
;     const size_t tstepA = 2 * hstepA, tstepB = 2 * hstepB;
;     const unsigned ldsw = (unsigned)wid * 1024u;
;     const int aoff = lds_byte(wr * 64 + fr, fq * 8), boff = lds_byte(wc * 32 + fr, fq * 8);
;     ...
;     Unit cur, nxt; int ui = 0;
;     if (!S.next(0, cur)) return;
;     f32x4 acc[2][2][4][2];
; #pragma unroll
;     for (int a = 0; a < 2; ++a)
; #pragma unroll
;         for (int b = 0; b < 2; ++b)
; #pragma unroll
;             for (int m = 0; m < 4; ++m)
; #pragma unroll
;                 for (int n = 0; n < 2; ++n) acc[a][b][m][n] = (f32x4){0.f, 0.f, 0.f, 0.f};
;     bf16x8 At[4][2], B0[2][2], B1[2][2];
;     const char* cA = (const char*)g.A + (size_t)g.mapA.src(cur.pm) * tstepA + (size_t)cur.pn * g.a_pn_step;
;     const char* cB = (const char*)g.Bt + (size_t)g.mapB.src(cur.pn) * tstepB;
;     PG8_STAGE(PG8_SB(0, 0), cB, voffB); PG8_STAGE(PG8_SA(0, 0), cA, voffA); PG8_STAGE(PG8_SB(0, 1), cB + hstepB, voffB); PG8_STAGE(PG8_SA(0, 1), cA + hstepA, voffA);
;     if (wr == 1) PG8_BAR;
.LBB0_321:
	v_readlane_b32 s0, v254, 32
	s_waitcnt vmcnt(2)
	v_mov_b32_e32 v8, v210
	v_readlane_b32 s1, v254, 33
	s_lshl_b32 s68, s4, 4
	s_andn2_b64 vcc, exec, s[0:1]
	v_readfirstlane_b32 s0, v8
	s_cbranch_vccnz .LBB0_369
	v_lshlrev_b32_e32 v1, 4, v8
	v_add_u32_e32 v3, 0x2000, v1
	v_ashrrev_i32_e32 v2, 31, v3
	v_lshrrev_b32_e32 v2, 22, v2
	v_add_u32_e32 v2, v3, v2
	v_ashrrev_i32_e32 v2, 10, v2
	v_mul_i32_i24_e32 v4, 0x400, v2
	v_sub_u32_e32 v3, v3, v4
	v_lshrrev_b32_e32 v4, 4, v3
	v_bitop3_b32 v4, v4, v3, 32 bitop3:0x6c
	v_ashrrev_i32_e32 v3, 31, v4
	v_lshrrev_b32_e32 v3, 26, v3
	v_add_u32_e32 v5, v4, v3
	v_lshlrev_b32_e32 v6, 3, v2
	v_ashrrev_i32_e32 v3, 6, v5
	v_and_b32_e32 v6, -16, v6
	v_add_u32_e32 v6, v3, v6
	v_and_b32_e32 v7, 3, v3
	s_mov_b32 s5, 0x1fffe0
	v_lshrrev_b32_e32 v9, 2, v6
	v_lshlrev_b32_e32 v10, 1, v6
	v_and_b32_e32 v5, 0xc0, v5
	v_and_or_b32 v7, v6, s5, v7
	v_and_b32_e32 v9, 4, v9
	v_and_b32_e32 v10, 24, v10
	v_sub_u32_e32 v4, v4, v5
	v_or3_b32 v7, v7, v9, v10
	v_lshlrev_b32_e32 v9, 5, v2
	v_ashrrev_i16_sdwa v4, v219, sext(v4) dst_sel:DWORD dst_unused:UNUSED_PAD src0_sel:DWORD src1_sel:BYTE_0
	v_and_b32_e32 v9, 32, v9
	v_bfe_i32 v4, v4, 0, 16
	v_add_lshl_u32 v5, v9, v4, 1
	v_lshl_add_u32 v180, v7, 11, v5
	v_lshl_add_u32 v182, v6, 11, v5
	v_bfe_i32 v5, v8, 27, 1
	v_lshrrev_b32_e32 v5, 22, v5
	v_add_u32_e32 v5, v1, v5
	v_and_b32_e32 v5, 0xfffffc00, v5
	v_sub_u32_e32 v1, v1, v5
	v_lshrrev_b32_e32 v5, 4, v1
	v_bitop3_b32 v7, v5, v1, 32 bitop3:0x6c
	v_ashrrev_i32_e32 v1, 31, v1
	v_lshrrev_b32_e32 v1, 26, v1
	v_add_u32_e32 v1, v7, v1
	v_ashrrev_i32_e32 v5, 6, v1
	v_ashrrev_i32_e32 v1, 31, v8
	v_lshrrev_b32_e32 v1, 26, v1
	v_add_u32_e32 v1, v8, v1
	v_ashrrev_i32_e32 v6, 6, v1
	v_lshlrev_b32_e32 v1, 3, v6
	v_and_b32_e32 v1, -16, v1
	v_add_u32_e32 v1, v5, v1
	v_and_b32_e32 v9, 3, v5
	v_lshrrev_b32_e32 v10, 2, v1
	v_lshlrev_b32_e32 v11, 1, v1
	v_and_or_b32 v9, v1, s5, v9
	v_and_b32_e32 v10, 4, v10
	v_and_b32_e32 v11, 24, v11
	s_lshl_b32 s4, s4, 7
	s_ashr_i32 s3, s0, 6
	v_or3_b32 v9, v9, v10, v11
	v_mul_i32_i24_e32 v11, 64, v5
	s_or_b32 s18, s4, 16
	v_readlane_b32 s4, v254, 51
	s_ashr_i32 s2, s0, 8
	s_lshl_b32 s1, s3, 10
	v_sub_u32_e32 v7, v7, v11
	v_readlane_b32 s5, v254, 52
	v_lshlrev_b32_e32 v10, 5, v6
	v_ashrrev_i16_sdwa v7, v219, sext(v7) dst_sel:DWORD dst_unused:UNUSED_PAD src0_sel:DWORD src1_sel:BYTE_0
	s_and_b64 s[4:5], s[4:5], exec
	v_and_b32_e32 v10, 32, v10
	v_bfe_i32 v7, v7, 0, 16
	s_cselect_b32 s4, s68, s18
	v_readlane_b32 s5, v254, 50
	v_add_lshl_u32 v10, v10, v7, 1
	s_add_i32 s4, s4, s5
	s_add_i32 s24, s1, 0
	v_lshl_add_u32 v184, v9, 11, v10
	s_ashr_i32 s5, s4, 31
	s_add_i32 m0, s24, 0x10000
	s_lshl_b64 s[4:5], s[4:5], 19
	global_load_lds_dwordx4 v184, s[8:9]
	s_add_i32 m0, s24, 0x12000
	s_add_u32 s60, s22, s4
	v_lshl_add_u32 v186, v1, 11, v10
	global_load_lds_dwordx4 v180, s[8:9]
	s_addc_u32 s61, s23, s5
	s_mov_b32 m0, s24
	s_add_i32 s25, s24, 0x2000
	global_load_lds_dwordx4 v186, s[60:61]
	s_mov_b32 m0, s25
	s_nop 0
	global_load_lds_dwordx4 v182, s[60:61]
	s_add_i32 m0, s24, 0x14000
	s_nop 0
	global_load_lds_dwordx4 v184, s[26:27]
	s_add_i32 m0, s24, 0x16000
	s_add_u32 s4, s60, 0x40000
	s_addc_u32 s5, s61, 0
	s_add_i32 s31, s24, 0x4000
	global_load_lds_dwordx4 v180, s[26:27]
	s_mov_b32 m0, s31
	s_add_i32 s36, s24, 0x6000
	global_load_lds_dwordx4 v186, s[4:5]
	s_mov_b32 m0, s36
	s_cmp_lg_u32 s2, 1
	global_load_lds_dwordx4 v182, s[4:5]
	s_setprio 1
	s_cbranch_scc1 .LBB0_324
	s_barrier
	s_setprio 0

; __device__ __forceinline__ int opaque_tid() { int t = threadIdx.x; asm volatile("" : "+v"(t)); return t; }
; #define PG8_STAGE(bufoff, gbase, voff) do { _Pragma("unroll") for (int _i = 0; _i < 2; ++_i) \
;         __builtin_amdgcn_global_load_lds((const unsigned*)((const char*)(gbase) + (voff)[_i]), (LAS unsigned*)(lds + (bufoff) + ldsw + _i * 8192), 16, 0, 0); } while (0)
; #define PG8_BAR __builtin_amdgcn_s_barrier()
; template <class Epi>
; __device__ __forceinline__ void gemm_phase(LAS unsigned char* lds, const Gemm g, const Epi& E) {
;     const int tid = opaque_tid(), wid = __builtin_amdgcn_readfirstlane(tid >> 6), lane = tid & 63, wr = wid >> 2, wc = wid & 3, fr = lane & 15, fq = lane >> 4;
;     const int K = g.K, nt = K / BK;
;     StaticOrder S; S.init(g.M, g.N, (int)gridDim.x, (int)blockIdx.x);
;     unsigned voffA[2], voffB[2];
; #pragma unroll
;     for (int i = 0; i < 2; ++i) { int R, C; stage_rc(tid * 16 + i * 8192, R, C); const int Rb = Epi::PERM ? ((R & ~31) + perm32(R & 31)) : R;
;         voffA[i] = (unsigned)(R * g.lda + C) * 2u; voffB[i] = (unsigned)(Rb * g.ldb + C) * 2u; }
;     const size_t kstep = (size_t)(BK * 2);
;     const size_t hstepA = (size_t)HALF * g.lda * 2, hstepB = (size_t)HALF * g.ldb * 2;
;     const size_t tstepA = 2 * hstepA, tstepB = 2 * hstepB;
;     const unsigned ldsw = (unsigned)wid * 1024u;
;     const int aoff = lds_byte(wr * 64 + fr, fq * 8), boff = lds_byte(wc * 32 + fr, fq * 8);
;     ...
;     Unit cur, nxt; int ui = 0;
;     if (!S.next(0, cur)) return;
;     f32x4 acc[2][2][4][2];
; #pragma unroll
;     for (int a = 0; a < 2; ++a)
; #pragma unroll
;         for (int b = 0; b < 2; ++b)
; #pragma unroll
;             for (int m = 0; m < 4; ++m)
; #pragma unroll
;                 for (int n = 0; n < 2; ++n) acc[a][b][m][n] = (f32x4){0.f, 0.f, 0.f, 0.f};
;     bf16x8 At[4][2], B0[2][2], B1[2][2];
;     const char* cA = (const char*)g.A + (size_t)g.mapA.src(cur.pm) * tstepA + (size_t)cur.pn * g.a_pn_step;
;     const char* cB = (const char*)g.Bt + (size_t)g.mapB.src(cur.pn) * tstepB;
;     PG8_STAGE(PG8_SB(0, 0), cB, voffB); PG8_STAGE(PG8_SA(0, 0), cA, voffA); PG8_STAGE(PG8_SB(0, 1), cB + hstepB, voffB); PG8_STAGE(PG8_SA(0, 1), cA + hstepA, voffA);
;     if (wr == 1) PG8_BAR;
.LBB0_466:
	s_or_b64 exec, exec, s[2:3]
	s_waitcnt vmcnt(2)
	v_mov_b32_e32 v10, v210
	s_lshr_b32 s30, s1, 8
	s_lshr_b32 s76, s1, 5
	s_barrier
	s_cmp_ge_i32 s37, s76
	v_readfirstlane_b32 s1, v10
	s_cbranch_scc1 .LBB0_480
	v_lshlrev_b32_e32 v1, 4, v10
	v_add_u32_e32 v2, 0x2000, v1
	v_ashrrev_i32_e32 v3, 31, v2
	v_lshrrev_b32_e32 v3, 22, v3
	v_add_u32_e32 v3, v2, v3
	v_ashrrev_i32_e32 v11, 10, v3
	v_mul_i32_i24_e32 v3, 0x400, v11
	v_sub_u32_e32 v2, v2, v3
	v_lshrrev_b32_e32 v3, 4, v2
	v_bitop3_b32 v2, v3, v2, 32 bitop3:0x6c
	v_ashrrev_i32_e32 v3, 31, v2
	v_lshrrev_b32_e32 v3, 26, v3
	v_add_u32_e32 v3, v2, v3
	v_lshlrev_b32_e32 v4, 3, v11
	v_ashrrev_i32_e32 v12, 6, v3
	v_and_b32_e32 v4, -16, v4
	v_add_u32_e32 v4, v12, v4
	v_and_b32_e32 v5, 3, v12
	s_mov_b32 s4, 0x1fffe0
	v_lshrrev_b32_e32 v6, 2, v4
	v_lshlrev_b32_e32 v7, 1, v4
	v_and_b32_e32 v3, 0xc0, v3
	v_and_or_b32 v5, v4, s4, v5
	v_and_b32_e32 v6, 4, v6
	v_and_b32_e32 v7, 24, v7
	v_sub_u32_e32 v2, v2, v3
	v_or3_b32 v5, v5, v6, v7
	v_lshlrev_b32_e32 v6, 5, v11
	v_ashrrev_i16_sdwa v2, v219, sext(v2) dst_sel:DWORD dst_unused:UNUSED_PAD src0_sel:DWORD src1_sel:BYTE_0
	v_and_b32_e32 v6, 32, v6
	v_bfe_i32 v13, v2, 0, 16
	v_add_lshl_u32 v2, v6, v13, 1
	v_lshl_add_u32 v166, v5, 11, v2
	v_lshl_add_u32 v168, v4, 11, v2
	v_bfe_i32 v2, v10, 27, 1
	v_lshrrev_b32_e32 v2, 22, v2
	v_add_u32_e32 v2, v1, v2
	v_and_b32_e32 v2, 0xfffffc00, v2
	v_sub_u32_e32 v1, v1, v2
	v_lshrrev_b32_e32 v2, 4, v1
	v_bitop3_b32 v2, v2, v1, 32 bitop3:0x6c
	v_ashrrev_i32_e32 v1, 31, v1
	v_lshrrev_b32_e32 v1, 26, v1
	v_add_u32_e32 v1, v2, v1
	v_ashrrev_i32_e32 v14, 6, v1
	v_ashrrev_i32_e32 v1, 31, v10
	v_lshrrev_b32_e32 v1, 26, v1
	v_add_u32_e32 v1, v10, v1
	v_ashrrev_i32_e32 v15, 6, v1
	v_lshlrev_b32_e32 v1, 3, v15
	v_and_b32_e32 v1, -16, v1
	v_add_u32_e32 v1, v14, v1
	v_and_b32_e32 v3, 3, v14
	s_ashr_i32 s2, s1, 6
	v_and_or_b32 v3, v1, s4, v3
	v_readlane_b32 s4, v254, 46
	s_ashr_i32 s3, s1, 8
	s_lshl_b32 s18, s2, 10
	s_or_b32 s24, s30, 1
	v_readlane_b32 s5, v254, 47
	s_and_b64 s[4:5], s[4:5], exec
	s_cselect_b32 s4, s24, s30
	s_mul_i32 s4, s4, s80
	s_add_i32 s4, s4, s75
	s_ashr_i32 s5, s4, 31
	s_lshr_b32 s5, s5, 27
	s_add_i32 s5, s4, s5
	v_lshrrev_b32_e32 v4, 2, v1
	v_lshlrev_b32_e32 v5, 1, v1
	s_ashr_i32 s6, s5, 5
	v_and_b32_e32 v4, 4, v4
	v_and_b32_e32 v5, 24, v5
	s_lshl_b32 s6, s6, 2
	v_or3_b32 v3, v3, v4, v5
	v_mul_i32_i24_e32 v5, 64, v14
	s_sub_i32 s7, s30, s6
	v_sub_u32_e32 v2, v2, v5
	s_min_i32 s7, s7, 4
	v_ashrrev_i16_sdwa v2, v219, sext(v2) dst_sel:DWORD dst_unused:UNUSED_PAD src0_sel:DWORD src1_sel:BYTE_0
	s_abs_i32 s8, s7
	s_waitcnt vmcnt(1)
	v_bfe_i32 v16, v2, 0, 16
	v_cvt_f32_u32_e32 v2, s8
	v_lshlrev_b32_e32 v4, 5, v15
	v_and_b32_e32 v4, 32, v4
	v_add_lshl_u32 v4, v4, v16, 1
	v_lshl_add_u32 v172, v1, 11, v4
	v_rcp_iflag_f32_e32 v1, v2
	s_sub_i32 s10, 0, s8
	s_andn2_b32 s5, s5, 31
	s_sub_i32 s4, s4, s5
	v_mul_f32_e32 v1, 0x4f7ffffe, v1
	v_cvt_u32_f32_e32 v1, v1
	s_abs_i32 s9, s4
	s_xor_b32 s5, s4, s7
	s_ashr_i32 s5, s5, 31
	v_readfirstlane_b32 s11, v1
	s_mul_i32 s10, s10, s11
	s_mul_hi_u32 s10, s11, s10
	s_add_i32 s11, s11, s10
	s_mul_hi_u32 s10, s9, s11
	s_mul_i32 s11, s10, s8
	s_sub_i32 s9, s9, s11
	s_add_i32 s11, s10, 1
	s_sub_i32 s12, s9, s8
	s_cmp_ge_u32 s9, s8
	s_cselect_b32 s10, s11, s10
	s_cselect_b32 s9, s12, s9
	s_add_i32 s11, s10, 1
	s_cmp_ge_u32 s9, s8
	s_cselect_b32 s8, s11, s10
	s_xor_b32 s8, s8, s5
	s_sub_i32 s12, s8, s5
	s_mul_i32 s5, s12, s7
	s_sub_i32 s4, s4, s5
	s_add_i32 s52, s6, s4
	v_readlane_b32 s4, v255, 23
	v_readlane_b32 s5, v255, 24
	s_and_b64 s[4:5], s[4:5], exec
	v_readlane_b32 s4, v255, 27
	s_cselect_b32 s25, 32, -2.0
	s_cmp_ge_i32 s52, s4
	s_cselect_b32 s4, s25, 0
	s_add_i32 s4, s4, s52
	s_ashr_i32 s5, s4, 31
	s_ashr_i32 s13, s12, 31
	s_lshl_b64 s[4:5], s[4:5], 19
	s_lshl_b64 s[6:7], s[12:13], 19
	v_readlane_b32 s8, v255, 28
	s_add_u32 s16, s8, s6
	v_readlane_b32 s6, v255, 29
	s_addc_u32 s17, s6, s7
	s_add_i32 s13, s18, 0
	v_lshl_add_u32 v170, v3, 11, v4
	s_add_i32 m0, s13, 0x10000
	v_mov_b32_e32 v171, v0
	global_load_lds_dwordx4 v170, s[16:17]
	s_add_i32 m0, s13, 0x12000
	s_add_u32 s14, s22, s4
	global_load_lds_dwordx4 v166, s[16:17]
	s_addc_u32 s15, s23, s5
	s_mov_b32 m0, s13
	s_add_i32 s31, s13, 0x2000
	global_load_lds_dwordx4 v172, s[14:15]
	s_mov_b32 m0, s31
	s_add_u32 s4, s16, 0x40000
	global_load_lds_dwordx4 v168, s[14:15]
	s_addc_u32 s5, s17, 0
	s_add_i32 m0, s13, 0x14000
	v_mov_b32_e32 v167, v0
	global_load_lds_dwordx4 v170, s[4:5]
	s_add_i32 m0, s13, 0x16000
	v_mov_b32_e32 v173, v0
	global_load_lds_dwordx4 v166, s[4:5]
	s_add_u32 s4, s14, 0x40000
	s_addc_u32 s5, s15, 0
	s_add_i32 s36, s13, 0x4000
	s_mov_b32 m0, s36
	s_add_i32 s44, s13, 0x6000
	global_load_lds_dwordx4 v172, s[4:5]
	s_mov_b32 m0, s44
	v_mov_b32_e32 v169, v0
	global_load_lds_dwordx4 v168, s[4:5]
	v_lshl_add_u64 v[8:9], s[16:17], 0, v[170:171]
	v_lshl_add_u64 v[6:7], s[16:17], 0, v[166:167]
	v_lshl_add_u64 v[4:5], s[14:15], 0, v[172:173]
	s_cmp_lg_u32 s3, 1
	v_lshl_add_u64 v[2:3], s[14:15], 0, v[168:169]
	s_setprio 1
	s_cbranch_scc1 .LBB0_469
	s_barrier
	s_setprio 0

; __device__ __forceinline__ int opaque_tid() { int t = threadIdx.x; asm volatile("" : "+v"(t)); return t; }
; #define PG8_STAGE(bufoff, gbase, voff) do { _Pragma("unroll") for (int _i = 0; _i < 2; ++_i) \
;         __builtin_amdgcn_global_load_lds((const unsigned*)((const char*)(gbase) + (voff)[_i]), (LAS unsigned*)(lds + (bufoff) + ldsw + _i * 8192), 16, 0, 0); } while (0)
; #define PG8_BAR __builtin_amdgcn_s_barrier()
; template <class Epi>
; __device__ __forceinline__ void gemm_phase(LAS unsigned char* lds, const Gemm g, const Epi& E) {
;     const int tid = opaque_tid(), wid = __builtin_amdgcn_readfirstlane(tid >> 6), lane = tid & 63, wr = wid >> 2, wc = wid & 3, fr = lane & 15, fq = lane >> 4;
;     const int K = g.K, nt = K / BK;
;     StaticOrder S; S.init(g.M, g.N, (int)gridDim.x, (int)blockIdx.x);
;     unsigned voffA[2], voffB[2];
; #pragma unroll
;     for (int i = 0; i < 2; ++i) { int R, C; stage_rc(tid * 16 + i * 8192, R, C); const int Rb = Epi::PERM ? ((R & ~31) + perm32(R & 31)) : R;
;         voffA[i] = (unsigned)(R * g.lda + C) * 2u; voffB[i] = (unsigned)(Rb * g.ldb + C) * 2u; }
;     const size_t kstep = (size_t)(BK * 2);
;     const size_t hstepA = (size_t)HALF * g.lda * 2, hstepB = (size_t)HALF * g.ldb * 2;
;     const size_t tstepA = 2 * hstepA, tstepB = 2 * hstepB;
;     const unsigned ldsw = (unsigned)wid * 1024u;
;     const int aoff = lds_byte(wr * 64 + fr, fq * 8), boff = lds_byte(wc * 32 + fr, fq * 8);
;     ...
;     Unit cur, nxt; int ui = 0;
;     if (!S.next(0, cur)) return;
;     f32x4 acc[2][2][4][2];
; #pragma unroll
;     for (int a = 0; a < 2; ++a)
; #pragma unroll
;         for (int b = 0; b < 2; ++b)
; #pragma unroll
;             for (int m = 0; m < 4; ++m)
; #pragma unroll
;                 for (int n = 0; n < 2; ++n) acc[a][b][m][n] = (f32x4){0.f, 0.f, 0.f, 0.f};
;     bf16x8 At[4][2], B0[2][2], B1[2][2];
;     const char* cA = (const char*)g.A + (size_t)g.mapA.src(cur.pm) * tstepA + (size_t)cur.pn * g.a_pn_step;
;     const char* cB = (const char*)g.Bt + (size_t)g.mapB.src(cur.pn) * tstepB;
;     PG8_STAGE(PG8_SB(0, 0), cB, voffB); PG8_STAGE(PG8_SA(0, 0), cA, voffA); PG8_STAGE(PG8_SB(0, 1), cB + hstepB, voffB); PG8_STAGE(PG8_SA(0, 1), cA + hstepA, voffA);
;     if (wr == 1) PG8_BAR;
.LBB0_486:
	s_or_b64 exec, exec, s[2:3]
	v_mov_b32_e32 v8, v210
	s_lshr_b32 s76, s1, 6
	s_barrier
	s_cmp_ge_i32 s37, s76
	v_readfirstlane_b32 s1, v8
	s_cbranch_scc1 .LBB0_500
	v_lshlrev_b32_e32 v1, 4, v8
	v_add_u32_e32 v3, 0x2000, v1
	v_ashrrev_i32_e32 v2, 31, v3
	v_lshrrev_b32_e32 v2, 22, v2
	v_add_u32_e32 v2, v3, v2
	v_ashrrev_i32_e32 v2, 10, v2
	v_lshlrev_b32_e32 v4, 5, v2
	v_and_b32_e32 v5, 32, v4
	v_mul_i32_i24_e32 v4, 0x400, v2
	v_sub_u32_e32 v3, v3, v4
	v_lshrrev_b32_e32 v4, 4, v3
	v_bitop3_b32 v4, v4, v3, 32 bitop3:0x6c
	v_ashrrev_i32_e32 v3, 31, v4
	v_lshrrev_b32_e32 v3, 26, v3
	v_add_u32_e32 v6, v4, v3
	v_ashrrev_i32_e32 v3, 6, v6
	v_and_b32_e32 v6, 0xc0, v6
	v_sub_u32_e32 v4, v4, v6
	v_ashrrev_i16_sdwa v4, v219, sext(v4) dst_sel:DWORD dst_unused:UNUSED_PAD src0_sel:DWORD src1_sel:BYTE_0
	v_lshlrev_b32_e32 v6, 3, v2
	v_bfe_i32 v4, v4, 0, 16
	v_and_b32_e32 v6, 0xffff0, v6
	v_add_u32_e32 v5, v5, v4
	v_add_lshl_u32 v6, v3, v6, 12
	v_lshl_add_u32 v146, v5, 1, v6
	v_ashrrev_i32_e32 v5, 31, v8
	v_lshrrev_b32_e32 v5, 26, v5
	v_add_u32_e32 v5, v8, v5
	v_ashrrev_i32_e32 v5, 6, v5
	v_lshlrev_b32_e32 v6, 5, v5
	v_and_b32_e32 v9, 32, v6
	v_bfe_i32 v6, v8, 27, 1
	v_readlane_b32 s2, v255, 21
	v_lshrrev_b32_e32 v6, 22, v6
	v_readlane_b32 s3, v255, 22
	v_add_u32_e32 v6, v1, v6
	s_lshl_b64 s[2:3], s[2:3], 22
	v_readlane_b32 s4, v254, 40
	v_and_b32_e32 v6, 0xfffffc00, v6
	s_add_u32 s18, s4, s2
	v_readlane_b32 s2, v254, 41
	v_sub_u32_e32 v1, v1, v6
	v_readlane_b32 s4, v255, 26
	s_addc_u32 s24, s2, s3
	v_lshrrev_b32_e32 v6, 4, v1
	s_lshr_b32 s28, s4, 9
	v_readlane_b32 s4, v254, 49
	v_bitop3_b32 v7, v6, v1, 32 bitop3:0x6c
	v_ashrrev_i32_e32 v1, 31, v1
	s_or_b32 s4, s28, s4
	v_lshrrev_b32_e32 v1, 26, v1
	s_mul_i32 s4, s4, s80
	v_add_u32_e32 v1, v7, v1
	s_add_i32 s4, s4, s75
	v_ashrrev_i32_e32 v6, 6, v1
	s_ashr_i32 s5, s4, 31
	v_mul_i32_i24_e32 v1, 64, v6
	s_lshr_b32 s5, s5, 28
	v_sub_u32_e32 v1, v7, v1
	s_add_i32 s5, s4, s5
	v_ashrrev_i16_sdwa v1, v219, sext(v1) dst_sel:DWORD dst_unused:UNUSED_PAD src0_sel:DWORD src1_sel:BYTE_0
	s_ashr_i32 s6, s5, 4
	v_bfe_i32 v7, v1, 0, 16
	s_lshl_b32 s6, s6, 2
	v_add_u32_e32 v1, v9, v7
	v_lshlrev_b32_e32 v9, 3, v5
	s_sub_i32 s7, s30, s6
	v_and_b32_e32 v9, 0xffff0, v9
	s_min_i32 s7, s7, 4
	v_add_lshl_u32 v9, v6, v9, 12
	s_abs_i32 s9, s7
	v_lshl_add_u32 v148, v1, 1, v9
	v_cvt_f32_u32_e32 v1, s9
	s_sub_i32 s10, 0, s9
	s_and_b32 s5, s5, -16
	s_sub_i32 s4, s4, s5
	v_rcp_iflag_f32_e32 v1, v1
	s_abs_i32 s8, s4
	s_ashr_i32 s2, s1, 6
	s_xor_b32 s5, s4, s7
	v_mul_f32_e32 v1, 0x4f7ffffe, v1
	v_cvt_u32_f32_e32 v1, v1
	s_ashr_i32 s3, s1, 8
	s_lshl_b32 s25, s2, 10
	s_ashr_i32 s5, s5, 31
	v_readfirstlane_b32 s11, v1
	s_mul_i32 s10, s10, s11
	s_mul_hi_u32 s10, s11, s10
	s_add_i32 s11, s11, s10
	s_mul_hi_u32 s10, s8, s11
	s_mul_i32 s11, s10, s9
	s_sub_i32 s8, s8, s11
	s_add_i32 s11, s10, 1
	s_sub_i32 s12, s8, s9
	s_cmp_ge_u32 s8, s9
	s_cselect_b32 s10, s11, s10
	s_cselect_b32 s8, s12, s8
	s_add_i32 s11, s10, 1
	s_cmp_ge_u32 s8, s9
	s_cselect_b32 s8, s11, s10
	s_xor_b32 s8, s8, s5
	s_sub_i32 s10, s8, s5
	s_mul_i32 s5, s10, s7
	s_sub_i32 s4, s4, s5
	s_add_i32 s61, s6, s4
	v_readlane_b32 s4, v255, 23
	v_readlane_b32 s5, v255, 24
	s_and_b64 s[4:5], s[4:5], exec
	v_readlane_b32 s4, v255, 27
	s_cselect_b32 s29, 32, -2.0
	s_cmp_ge_i32 s61, s4
	s_cselect_b32 s4, s29, 0
	s_add_i32 s4, s4, s61
	s_ashr_i32 s5, s4, 31
	s_ashr_i32 s11, s10, 31
	s_lshl_b64 s[4:5], s[4:5], 20
	s_lshl_b64 s[6:7], s[10:11], 20
	s_add_u32 s14, s18, s6
	s_addc_u32 s15, s24, s7
	s_add_i32 s11, s25, 0
	s_add_i32 m0, s11, 0x10000
	s_nop 0
	global_load_lds_dwordx4 v148, s[14:15]
	s_add_i32 m0, s11, 0x12000
	s_add_u32 s12, s34, s4
	global_load_lds_dwordx4 v146, s[14:15]
	s_addc_u32 s13, s35, s5
	s_mov_b32 m0, s11
	s_add_i32 s31, s11, 0x2000
	global_load_lds_dwordx4 v148, s[12:13]
	s_mov_b32 m0, s31
	s_add_u32 s4, s14, 0x80000
	global_load_lds_dwordx4 v146, s[12:13]
	s_addc_u32 s5, s15, 0
	s_add_i32 m0, s11, 0x14000
	s_nop 0
	global_load_lds_dwordx4 v148, s[4:5]
	s_add_i32 m0, s11, 0x16000
	s_nop 0
	global_load_lds_dwordx4 v146, s[4:5]
	s_add_u32 s4, s12, 0x80000
	s_addc_u32 s5, s13, 0
	s_add_i32 s36, s11, 0x4000
	s_mov_b32 m0, s36
	s_add_i32 s44, s11, 0x6000
	global_load_lds_dwordx4 v148, s[4:5]
	s_mov_b32 m0, s44
	s_cmp_lg_u32 s3, 1
	global_load_lds_dwordx4 v146, s[4:5]
	s_setprio 1
	s_cbranch_scc1 .LBB0_489
	s_barrier
	s_setprio 0

; __device__ __forceinline__ int opaque_tid() { int t = threadIdx.x; asm volatile("" : "+v"(t)); return t; }
; #define PG8_STAGE(bufoff, gbase, voff) do { _Pragma("unroll") for (int _i = 0; _i < 2; ++_i) \
;         __builtin_amdgcn_global_load_lds((const unsigned*)((const char*)(gbase) + (voff)[_i]), (LAS unsigned*)(lds + (bufoff) + ldsw + _i * 8192), 16, 0, 0); } while (0)
; #define PG8_BAR __builtin_amdgcn_s_barrier()
; template <class Epi>
; __device__ __forceinline__ void gemm_phase(LAS unsigned char* lds, const Gemm g, const Epi& E) {
;     const int tid = opaque_tid(), wid = __builtin_amdgcn_readfirstlane(tid >> 6), lane = tid & 63, wr = wid >> 2, wc = wid & 3, fr = lane & 15, fq = lane >> 4;
;     const int K = g.K, nt = K / BK;
;     StaticOrder S; S.init(g.M, g.N, (int)gridDim.x, (int)blockIdx.x);
;     unsigned voffA[2], voffB[2];
; #pragma unroll
;     for (int i = 0; i < 2; ++i) { int R, C; stage_rc(tid * 16 + i * 8192, R, C); const int Rb = Epi::PERM ? ((R & ~31) + perm32(R & 31)) : R;
;         voffA[i] = (unsigned)(R * g.lda + C) * 2u; voffB[i] = (unsigned)(Rb * g.ldb + C) * 2u; }
;     const size_t kstep = (size_t)(BK * 2);
;     const size_t hstepA = (size_t)HALF * g.lda * 2, hstepB = (size_t)HALF * g.ldb * 2;
;     const size_t tstepA = 2 * hstepA, tstepB = 2 * hstepB;
;     const unsigned ldsw = (unsigned)wid * 1024u;
;     const int aoff = lds_byte(wr * 64 + fr, fq * 8), boff = lds_byte(wc * 32 + fr, fq * 8);
;     ...
;     Unit cur, nxt; int ui = 0;
;     if (!S.next(0, cur)) return;
;     f32x4 acc[2][2][4][2];
; #pragma unroll
;     for (int a = 0; a < 2; ++a)
; #pragma unroll
;         for (int b = 0; b < 2; ++b)
; #pragma unroll
;             for (int m = 0; m < 4; ++m)
; #pragma unroll
;                 for (int n = 0; n < 2; ++n) acc[a][b][m][n] = (f32x4){0.f, 0.f, 0.f, 0.f};
;     bf16x8 At[4][2], B0[2][2], B1[2][2];
;     const char* cA = (const char*)g.A + (size_t)g.mapA.src(cur.pm) * tstepA + (size_t)cur.pn * g.a_pn_step;
;     const char* cB = (const char*)g.Bt + (size_t)g.mapB.src(cur.pn) * tstepB;
;     PG8_STAGE(PG8_SB(0, 0), cB, voffB); PG8_STAGE(PG8_SA(0, 0), cA, voffA); PG8_STAGE(PG8_SB(0, 1), cB + hstepB, voffB); PG8_STAGE(PG8_SA(0, 1), cA + hstepA, voffA);
;     if (wr == 1) PG8_BAR;
.LBB0_516:
	s_or_b64 exec, exec, s[2:3]
	s_lshr_b32 s28, s1, 8
	v_mov_b32_e32 v8, v210
	s_mul_i32 s76, s28, 22
	s_barrier
	s_cmp_ge_i32 s37, s76
	v_readfirstlane_b32 s1, v8
	s_cbranch_scc1 .LBB0_530
	v_lshlrev_b32_e32 v1, 4, v8
	v_add_u32_e32 v3, 0x2000, v1
	v_ashrrev_i32_e32 v2, 31, v3
	v_lshrrev_b32_e32 v2, 22, v2
	v_add_u32_e32 v2, v3, v2
	v_ashrrev_i32_e32 v2, 10, v2
	v_mul_i32_i24_e32 v4, 0x400, v2
	v_sub_u32_e32 v3, v3, v4
	v_lshrrev_b32_e32 v4, 4, v3
	v_bitop3_b32 v4, v4, v3, 32 bitop3:0x6c
	v_ashrrev_i32_e32 v3, 31, v4
	v_lshrrev_b32_e32 v3, 26, v3
	v_add_u32_e32 v5, v4, v3
	v_lshlrev_b32_e32 v6, 3, v2
	v_readlane_b32 s3, v255, 20
	v_ashrrev_i32_e32 v3, 6, v5
	v_and_b32_e32 v6, -16, v6
	s_mul_hi_u32 s2, s3, 0xb00000
	s_mul_i32 s3, s3, 0xb00000
	v_readlane_b32 s4, v254, 42
	v_add_u32_e32 v6, v3, v6
	s_add_u32 s18, s4, s3
	v_and_b32_e32 v7, 3, v3
	s_mov_b32 s4, 0x1fffe0
	v_lshrrev_b32_e32 v9, 2, v6
	v_lshlrev_b32_e32 v10, 1, v6
	v_and_b32_e32 v5, 0xc0, v5
	v_and_or_b32 v7, v6, s4, v7
	v_and_b32_e32 v9, 4, v9
	v_and_b32_e32 v10, 24, v10
	v_sub_u32_e32 v4, v4, v5
	v_or3_b32 v7, v7, v9, v10
	v_lshlrev_b32_e32 v9, 5, v2
	v_ashrrev_i16_sdwa v4, v219, sext(v4) dst_sel:DWORD dst_unused:UNUSED_PAD src0_sel:DWORD src1_sel:BYTE_0
	v_and_b32_e32 v9, 32, v9
	v_bfe_i32 v4, v4, 0, 16
	v_add_lshl_u32 v5, v9, v4, 1
	v_lshl_add_u32 v130, v7, 11, v5
	v_lshl_add_u32 v132, v6, 11, v5
	v_bfe_i32 v5, v8, 27, 1
	v_lshrrev_b32_e32 v5, 22, v5
	v_add_u32_e32 v5, v1, v5
	v_and_b32_e32 v5, 0xfffffc00, v5
	v_sub_u32_e32 v1, v1, v5
	v_lshrrev_b32_e32 v5, 4, v1
	v_bitop3_b32 v7, v5, v1, 32 bitop3:0x6c
	v_ashrrev_i32_e32 v1, 31, v1
	v_lshrrev_b32_e32 v1, 26, v1
	v_add_u32_e32 v1, v7, v1
	v_ashrrev_i32_e32 v5, 6, v1
	v_ashrrev_i32_e32 v1, 31, v8
	v_lshrrev_b32_e32 v1, 26, v1
	v_add_u32_e32 v1, v8, v1
	v_ashrrev_i32_e32 v6, 6, v1
	v_lshlrev_b32_e32 v1, 3, v6
	v_and_b32_e32 v1, -16, v1
	v_readlane_b32 s3, v254, 43
	v_add_u32_e32 v1, v5, v1
	v_and_b32_e32 v9, 3, v5
	s_addc_u32 s24, s3, s2
	s_ashr_i32 s2, s1, 6
	v_and_or_b32 v9, v1, s4, v9
	s_lshr_b32 s29, s76, 3
	v_readlane_b32 s4, v254, 46
	s_ashr_i32 s3, s1, 8
	s_lshl_b32 s25, s2, 10
	s_or_b32 s30, s29, 1
	v_readlane_b32 s5, v254, 47
	s_and_b64 s[4:5], s[4:5], exec
	s_cselect_b32 s4, s30, s29
	s_mul_i32 s4, s4, s80
	s_add_i32 s4, s4, s75
	s_mul_hi_i32 s5, s4, 0x2e8ba2e9
	s_lshr_b32 s6, s5, 31
	s_ashr_i32 s5, s5, 4
	s_add_i32 s5, s5, s6
	s_lshl_b32 s6, s5, 2
	v_lshrrev_b32_e32 v10, 2, v1
	v_lshlrev_b32_e32 v11, 1, v1
	s_sub_i32 s7, s28, s6
	v_and_b32_e32 v10, 4, v10
	v_and_b32_e32 v11, 24, v11
	s_min_i32 s7, s7, 4
	v_or3_b32 v9, v9, v10, v11
	v_mul_i32_i24_e32 v11, 64, v5
	s_abs_i32 s8, s7
	v_sub_u32_e32 v7, v7, v11
	v_cvt_f32_u32_e32 v11, s8
	v_lshlrev_b32_e32 v10, 5, v6
	v_ashrrev_i16_sdwa v7, v219, sext(v7) dst_sel:DWORD dst_unused:UNUSED_PAD src0_sel:DWORD src1_sel:BYTE_0
	v_and_b32_e32 v10, 32, v10
	v_bfe_i32 v7, v7, 0, 16
	v_add_lshl_u32 v10, v10, v7, 1
	v_lshl_add_u32 v136, v1, 11, v10
	v_rcp_iflag_f32_e32 v1, v11
	s_sub_i32 s10, 0, s8
	s_mulk_i32 s5, 0x58
	s_sub_i32 s4, s4, s5
	v_mul_f32_e32 v1, 0x4f7ffffe, v1
	v_cvt_u32_f32_e32 v1, v1
	s_abs_i32 s9, s4
	s_xor_b32 s5, s4, s7
	s_ashr_i32 s5, s5, 31
	v_readfirstlane_b32 s11, v1
	s_mul_i32 s10, s10, s11
	s_mul_hi_u32 s10, s11, s10
	s_add_i32 s11, s11, s10
	s_mul_hi_u32 s10, s9, s11
	s_mul_i32 s11, s10, s8
	s_sub_i32 s9, s9, s11
	s_add_i32 s11, s10, 1
	s_sub_i32 s12, s9, s8
	s_cmp_ge_u32 s9, s8
	s_cselect_b32 s10, s11, s10
	s_cselect_b32 s9, s12, s9
	s_add_i32 s11, s10, 1
	s_cmp_ge_u32 s9, s8
	s_cselect_b32 s8, s11, s10
	s_xor_b32 s8, s8, s5
	s_sub_i32 s10, s8, s5
	s_mul_i32 s5, s10, s7
	s_sub_i32 s4, s4, s5
	s_add_i32 s64, s6, s4
	v_readlane_b32 s4, v255, 23
	v_readlane_b32 s5, v255, 24
	s_and_b64 s[4:5], s[4:5], exec
	v_readlane_b32 s4, v255, 27
	s_cselect_b32 s31, 32, -2.0
	s_cmp_ge_i32 s64, s4
	s_cselect_b32 s4, s31, 0
	s_add_i32 s4, s4, s64
	s_ashr_i32 s5, s4, 31
	s_ashr_i32 s11, s10, 31
	s_lshl_b64 s[4:5], s[4:5], 19
	s_lshl_b64 s[6:7], s[10:11], 19
	s_add_u32 s14, s18, s6
	s_addc_u32 s15, s24, s7
	s_add_i32 s11, s25, 0
	v_lshl_add_u32 v134, v9, 11, v10
	s_add_i32 m0, s11, 0x10000
	s_nop 0
	global_load_lds_dwordx4 v134, s[14:15]
	s_add_i32 m0, s11, 0x12000
	s_add_u32 s12, s22, s4
	global_load_lds_dwordx4 v130, s[14:15]
	s_addc_u32 s13, s23, s5
	s_mov_b32 m0, s11
	s_add_i32 s36, s11, 0x2000
	global_load_lds_dwordx4 v136, s[12:13]
	s_mov_b32 m0, s36
	s_add_u32 s4, s14, 0x40000
	global_load_lds_dwordx4 v132, s[12:13]
	s_addc_u32 s5, s15, 0
	s_add_i32 m0, s11, 0x14000
	s_nop 0
	global_load_lds_dwordx4 v134, s[4:5]
	s_add_i32 m0, s11, 0x16000
	s_nop 0
	global_load_lds_dwordx4 v130, s[4:5]
	s_add_u32 s4, s12, 0x40000
	s_addc_u32 s5, s13, 0
	s_add_i32 s44, s11, 0x4000
	s_mov_b32 m0, s44
	s_add_i32 s50, s11, 0x6000
	global_load_lds_dwordx4 v136, s[4:5]
	s_mov_b32 m0, s50
	s_cmp_lg_u32 s3, 1
	global_load_lds_dwordx4 v132, s[4:5]
	s_setprio 1
	s_cbranch_scc1 .LBB0_519
	s_barrier
	s_setprio 0

; __device__ __forceinline__ int opaque_tid() { int t = threadIdx.x; asm volatile("" : "+v"(t)); return t; }
; #define PG8_STAGE(bufoff, gbase, voff) do { _Pragma("unroll") for (int _i = 0; _i < 2; ++_i) \
;         __builtin_amdgcn_global_load_lds((const unsigned*)((const char*)(gbase) + (voff)[_i]), (LAS unsigned*)(lds + (bufoff) + ldsw + _i * 8192), 16, 0, 0); } while (0)
; #define PG8_BAR __builtin_amdgcn_s_barrier()
; template <class Epi>
; __device__ __forceinline__ void gemm_phase(LAS unsigned char* lds, const Gemm g, const Epi& E) {
;     const int tid = opaque_tid(), wid = __builtin_amdgcn_readfirstlane(tid >> 6), lane = tid & 63, wr = wid >> 2, wc = wid & 3, fr = lane & 15, fq = lane >> 4;
;     const int K = g.K, nt = K / BK;
;     StaticOrder S; S.init(g.M, g.N, (int)gridDim.x, (int)blockIdx.x);
;     unsigned voffA[2], voffB[2];
; #pragma unroll
;     for (int i = 0; i < 2; ++i) { int R, C; stage_rc(tid * 16 + i * 8192, R, C); const int Rb = Epi::PERM ? ((R & ~31) + perm32(R & 31)) : R;
;         voffA[i] = (unsigned)(R * g.lda + C) * 2u; voffB[i] = (unsigned)(Rb * g.ldb + C) * 2u; }
;     const size_t kstep = (size_t)(BK * 2);
;     const size_t hstepA = (size_t)HALF * g.lda * 2, hstepB = (size_t)HALF * g.ldb * 2;
;     const size_t tstepA = 2 * hstepA, tstepB = 2 * hstepB;
;     const unsigned ldsw = (unsigned)wid * 1024u;
;     const int aoff = lds_byte(wr * 64 + fr, fq * 8), boff = lds_byte(wc * 32 + fr, fq * 8);
;     ...
;     Unit cur, nxt; int ui = 0;
;     if (!S.next(0, cur)) return;
;     f32x4 acc[2][2][4][2];
; #pragma unroll
;     for (int a = 0; a < 2; ++a)
; #pragma unroll
;         for (int b = 0; b < 2; ++b)
; #pragma unroll
;             for (int m = 0; m < 4; ++m)
; #pragma unroll
;                 for (int n = 0; n < 2; ++n) acc[a][b][m][n] = (f32x4){0.f, 0.f, 0.f, 0.f};
;     bf16x8 At[4][2], B0[2][2], B1[2][2];
;     const char* cA = (const char*)g.A + (size_t)g.mapA.src(cur.pm) * tstepA + (size_t)cur.pn * g.a_pn_step;
;     const char* cB = (const char*)g.Bt + (size_t)g.mapB.src(cur.pn) * tstepB;
;     PG8_STAGE(PG8_SB(0, 0), cB, voffB); PG8_STAGE(PG8_SA(0, 0), cA, voffA); PG8_STAGE(PG8_SB(0, 1), cB + hstepB, voffB); PG8_STAGE(PG8_SA(0, 1), cA + hstepA, voffA);
;     if (wr == 1) PG8_BAR;
.LBB0_536:
	s_or_b64 exec, exec, s[2:3]
	v_mov_b32_e32 v10, v210
	s_lshr_b32 s76, s1, 6
	s_barrier
	s_cmp_ge_i32 s37, s76
	s_mov_b32 s5, s1
	v_readfirstlane_b32 s1, v10
	v_readlane_b32 s4, v255, 20
	s_cbranch_scc1 .LBB0_552
	v_lshlrev_b32_e32 v1, 4, v10
	v_add_u32_e32 v3, 0x2000, v1
	v_ashrrev_i32_e32 v2, 31, v3
	v_lshrrev_b32_e32 v2, 22, v2
	v_add_u32_e32 v2, v3, v2
	v_ashrrev_i32_e32 v2, 10, v2
	v_mul_i32_i24_e32 v4, 0x400, v2
	v_sub_u32_e32 v3, v3, v4
	v_lshrrev_b32_e32 v4, 4, v3
	v_bitop3_b32 v5, v4, v3, 32 bitop3:0x6c
	v_ashrrev_i32_e32 v3, 31, v5
	v_lshrrev_b32_e32 v3, 26, v3
	v_add_u32_e32 v6, v5, v3
	v_ashrrev_i32_e32 v3, 6, v6
	v_and_b32_e32 v6, 0xc0, v6
	v_sub_u32_e32 v5, v5, v6
	v_bfe_i32 v6, v10, 27, 1
	v_lshrrev_b32_e32 v6, 22, v6
	v_add_u32_e32 v6, v1, v6
	v_and_b32_e32 v6, 0xfffffc00, v6
	v_sub_u32_e32 v1, v1, v6
	v_lshrrev_b32_e32 v6, 4, v1
	v_lshlrev_b32_e32 v4, 3, v2
	v_bitop3_b32 v9, v6, v1, 32 bitop3:0x6c
	v_ashrrev_i32_e32 v1, 31, v1
	s_mul_hi_u32 s2, s4, 0x580000
	s_mul_i32 s3, s4, 0x580000
	v_readlane_b32 s4, v254, 44
	v_and_b32_e32 v4, 0xfffff0, v4
	v_lshrrev_b32_e32 v1, 26, v1
	s_add_u32 s16, s4, s3
	v_add_u32_e32 v4, v3, v4
	s_movk_i32 s4, 0xb00
	v_add_u32_e32 v1, v9, v1
	v_mul_lo_u32 v7, v4, s4
	v_lshlrev_b32_e32 v4, 5, v2
	v_ashrrev_i32_e32 v6, 6, v1
	v_ashrrev_i32_e32 v1, 31, v10
	v_and_b32_e32 v4, 32, v4
	v_ashrrev_i16_sdwa v5, v219, sext(v5) dst_sel:DWORD dst_unused:UNUSED_PAD src0_sel:DWORD src1_sel:BYTE_0
	v_lshrrev_b32_e32 v1, 26, v1
	v_or_b32_e32 v7, v7, v4
	v_bfe_i32 v5, v5, 0, 16
	v_add_u32_e32 v1, v10, v1
	v_add_lshl_u32 v146, v7, v5, 1
	v_ashrrev_i32_e32 v7, 6, v1
	v_lshlrev_b32_e32 v1, 3, v7
	v_and_b32_e32 v1, 0xfffff0, v1
	v_readlane_b32 s3, v254, 45
	v_add_u32_e32 v1, v6, v1
	s_addc_u32 s17, s3, s2
	v_mul_lo_u32 v1, v1, s4
	s_lshr_b32 s24, s5, 9
	v_readlane_b32 s4, v254, 49
	s_or_b32 s4, s24, s4
	s_mul_i32 s4, s4, s80
	s_add_i32 s4, s4, s75
	s_ashr_i32 s5, s4, 31
	s_lshr_b32 s5, s5, 28
	s_add_i32 s5, s4, s5
	s_ashr_i32 s6, s5, 4
	s_lshl_b32 s6, s6, 2
	s_sub_i32 s7, s28, s6
	s_min_i32 s7, s7, 4
	v_mul_i32_i24_e32 v11, 64, v6
	s_abs_i32 s8, s7
	v_sub_u32_e32 v9, v9, v11
	v_cvt_f32_u32_e32 v11, s8
	v_lshlrev_b32_e32 v8, 5, v7
	v_and_b32_e32 v8, 32, v8
	v_ashrrev_i16_sdwa v9, v219, sext(v9) dst_sel:DWORD dst_unused:UNUSED_PAD src0_sel:DWORD src1_sel:BYTE_0
	v_or_b32_e32 v1, v1, v8
	v_bfe_i32 v9, v9, 0, 16
	v_add_lshl_u32 v148, v1, v9, 1
	v_rcp_iflag_f32_e32 v1, v11
	s_sub_i32 s10, 0, s8
	s_and_b32 s5, s5, -16
	s_sub_i32 s4, s4, s5
	v_mul_f32_e32 v1, 0x4f7ffffe, v1
	v_cvt_u32_f32_e32 v1, v1
	s_abs_i32 s9, s4
	s_ashr_i32 s2, s1, 6
	s_xor_b32 s5, s4, s7
	v_readfirstlane_b32 s11, v1
	s_mul_i32 s10, s10, s11
	s_mul_hi_u32 s10, s11, s10
	s_add_i32 s11, s11, s10
	s_mul_hi_u32 s10, s9, s11
	s_mul_i32 s11, s10, s8
	s_sub_i32 s9, s9, s11
	s_ashr_i32 s3, s1, 8
	s_lshl_b32 s18, s2, 10
	s_ashr_i32 s5, s5, 31
	s_add_i32 s11, s10, 1
	s_sub_i32 s12, s9, s8
	s_cmp_ge_u32 s9, s8
	s_cselect_b32 s10, s11, s10
	s_cselect_b32 s9, s12, s9
	s_add_i32 s11, s10, 1
	s_cmp_ge_u32 s9, s8
	s_cselect_b32 s8, s11, s10
	s_xor_b32 s8, s8, s5
	s_sub_i32 s61, s8, s5
	s_mul_i32 s5, s61, s7
	s_sub_i32 s4, s4, s5
	s_add_i32 s64, s6, s4
	v_readlane_b32 s4, v255, 23
	v_readlane_b32 s5, v255, 24
	s_and_b64 s[4:5], s[4:5], exec
	v_readlane_b32 s4, v255, 27
	s_cselect_b32 s25, 32, -2.0
	s_cmp_ge_i32 s64, s4
	s_cselect_b32 s4, s25, 0
	s_add_i32 s4, s4, s64
	s_mul_i32 s7, s61, 0x160000
	s_mul_hi_i32 s6, s61, 0x160000
	s_add_u32 s10, s16, s7
	s_addc_u32 s11, s17, s6
	s_add_i32 s29, s18, 0
	s_add_i32 m0, s29, 0x10000
	s_mul_hi_i32 s5, s4, 0x160000
	s_mul_i32 s4, s4, 0x160000
	global_load_lds_dwordx4 v148, s[10:11]
	s_add_i32 m0, s29, 0x12000
	s_add_u32 s8, s34, s4
	global_load_lds_dwordx4 v146, s[10:11]
	s_addc_u32 s9, s35, s5
	s_mov_b32 m0, s29
	s_add_i32 s30, s29, 0x2000
	global_load_lds_dwordx4 v148, s[8:9]
	s_mov_b32 m0, s30
	s_add_u32 s4, s10, 0xb0000
	global_load_lds_dwordx4 v146, s[8:9]
	s_addc_u32 s5, s11, 0
	s_add_i32 m0, s29, 0x14000
	s_nop 0
	global_load_lds_dwordx4 v148, s[4:5]
	s_add_i32 m0, s29, 0x16000
	s_nop 0
	global_load_lds_dwordx4 v146, s[4:5]
	s_add_u32 s4, s8, 0xb0000
	s_addc_u32 s5, s9, 0
	s_add_i32 s31, s29, 0x4000
	s_mov_b32 m0, s31
	s_add_i32 s36, s29, 0x6000
	global_load_lds_dwordx4 v148, s[4:5]
	s_mov_b32 m0, s36
	s_cmp_lg_u32 s3, 1
	global_load_lds_dwordx4 v146, s[4:5]
	s_setprio 1
	s_cbranch_scc1 .LBB0_539
	s_barrier
	s_setprio 0
